# prologue: half of each XCD's blocks run the input LayerNorm before their s5_item table builds (memory/compute overlap), LN loop gamma/beta hoisted and row loads double-buffered
# speedup vs baseline: 1.0076x; 1.0076x over previous
_Z3fwd4Args:
	s_mov_b32 s32, 0
	s_load_dwordx8 s[4:11], s[0:1], 0x100
	s_load_dwordx2 s[78:79], s[0:1], 0x120
	s_load_dwordx4 s[24:27], s[0:1], 0x128
	v_and_b32_e32 v181, 0x3ff, v0
	s_mov_b32 s68, s2
	v_cmp_gt_u32_e32 vcc, 16, v181
	s_waitcnt lgkmcnt(0)
	v_writelane_b32 v252, s4, 0
	s_nop 1
	v_writelane_b32 v252, s5, 1
	v_writelane_b32 v252, s6, 2
	v_writelane_b32 v252, s7, 3
	v_writelane_b32 v252, s8, 4
	v_writelane_b32 v252, s9, 5
	v_writelane_b32 v252, s10, 6
	v_writelane_b32 v252, s11, 7
	s_and_saveexec_b64 s[2:3], vcc
	v_lshl_add_u32 v1, v181, 2, 0
	v_add_u32_e32 v1, 0x26800, v1
	v_mov_b32_e32 v2, 0
	ds_write_b32 v1, v2
	s_or_b64 exec, exec, s[2:3]
	s_add_u32 s2, s78, 0x1000
	s_addc_u32 s3, s79, 0
	s_cmp_eq_u32 s26, 0
	s_cselect_b64 s[4:5], -1, 0
	v_writelane_b32 v252, s4, 8
	s_mov_b32 s8, 0
	s_and_b64 vcc, exec, s[4:5]
	v_writelane_b32 v252, s5, 9
	v_cmp_eq_u32_e64 s[4:5], 0, v181
	s_waitcnt lgkmcnt(0)
	s_barrier
	s_cbranch_vccnz .LBB0_7
	s_getreg_b32 s6, hwreg(HW_REG_XCC_ID, 0, 4)
	s_and_b32 s8, s6, 15
	s_and_saveexec_b64 s[6:7], s[4:5]
	s_cbranch_execz .LBB0_6
	s_mov_b64 s[4:5], exec
	v_mbcnt_lo_u32_b32 v1, s4, 0
	v_mbcnt_hi_u32_b32 v1, s5, v1
	v_cmp_eq_u32_e32 vcc, 0, v1
	s_and_b64 s[10:11], exec, vcc
	s_mov_b64 exec, s[10:11]
	s_cbranch_execz .LBB0_6
	s_lshl_b32 s9, s8, 8
	s_bcnt1_i32_b64 s4, s[4:5]
	v_mov_b32_e32 v1, s9
	v_mov_b32_e32 v2, s4
	global_atomic_add v1, v2, s[2:3] offset:1024

.LBB0_1683:
	s_or_b64 exec, exec, s[0:1]
	s_mov_b32 s23, s68
	s_waitcnt vmcnt(0)
	s_barrier
	s_bitcmp1_b32 s68, 3
	s_cbranch_scc0 .Lp0_norm
	s_cmp_lg_u32 s32, 0
	s_cbranch_scc1 .Lp0_norm
	s_mov_b32 s32, 1
	v_mov_b32_e32 v95, v0
	v_mov_b32_e32 v96, v1
	v_mov_b32_e32 v97, v14
	v_mov_b32_e32 v98, v15
	v_mov_b32_e32 v99, v29
	v_lshlrev_b32_e32 v2, 3, v0
	s_branch .LBB0_1728
.Lp0_norm:
	s_cmpk_gt_i32 s23, 0x1ff
	v_lshlrev_b32_e32 v2, 3, v0
	s_cbranch_scc1 .LBB0_1728
	s_movk_i32 s0, 0x880
	v_cmp_gt_i32_e64 s[38:39], s0, v1
	s_movk_i32 s0, 0x800
	v_cmp_gt_i32_e64 s[40:41], s0, v1
	s_movk_i32 s0, 0x2000
	v_cmp_gt_i32_e64 s[42:43], s0, v1
	v_and_b32_e32 v6, 0x1ff, v1
	s_movk_i32 s0, 0xff
	v_cmp_lt_u32_e64 s[44:45], s0, v6
	s_movk_i32 s0, 0x17f
	v_cmp_lt_u32_e64 s[46:47], s0, v6
	s_movk_i32 s0, 0x1000
	v_cmp_gt_i32_e64 s[50:51], s0, v1
	s_movk_i32 s0, 0x80
	v_cmp_gt_i32_e64 s[52:53], s0, v1
	s_movk_i32 s0, 0x2200
	v_and_b32_e32 v4, 15, v1
	v_and_b32_e32 v5, 1, v1
	v_readlane_b32 s1, v253, 56
	v_and_b32_e32 v8, 0xff, v1
	v_bfe_u32 v17, v1, 4, 4
	v_mul_lo_u32 v7, v14, s0
	s_add_i32 s34, 0, 0x12000
	v_readlane_b32 s0, v253, 57
	v_cndmask_b32_e64 v3, 0, 16, s[46:47]
	v_cmp_eq_u32_e64 s[48:49], 0, v5
	v_bfe_u32 v5, v1, 4, 5
	v_lshl_add_u32 v16, v4, 3, s1
	v_xor_b32_e32 v18, 15, v17
	v_add3_u32 v19, s34, v7, v2
	v_lshlrev_b32_e32 v20, 4, v14
	v_add_u32_e32 v21, s34, v15
	v_add_u32_e32 v22, s1, v15
	v_add_u32_e32 v23, s0, v15
	v_lshlrev_b32_e32 v6, 1, v6
	v_lshlrev_b32_e32 v8, 1, v8
	s_branch .LBB0_1686

.LBB0_1728:
	s_cmp_eq_u32 s32, 2
	s_cbranch_scc1 .Lp0_ln_done
	s_mov_b64 s[0:1], 0
	s_mov_b64 s[2:3], 0
	s_mov_b32 s2, 0x8000
	s_mov_b64 s[20:21], 0
	v_cmp_gt_i32_e32 vcc, s2, v28
	s_and_saveexec_b64 s[2:3], vcc
	s_mov_b32 s34, 0x800000
	s_mov_b32 s40, 0x3a800000
	s_cbranch_execz .LBB0_1731
	s_add_u32 s24, s78, s20
	s_addc_u32 s25, s79, s21
	v_mov_b32_e32 v3, v169
	v_lshlrev_b32_e32 v168, 4, v0
	v_lshl_add_u64 v[0:1], s[24:25], 0, v[2:3]
	s_mov_b64 s[24:25], 0x6400000
	v_ashrrev_i32_e32 v29, 31, v28
	v_lshl_add_u64 v[32:33], v[0:1], 0, s[24:25]
	v_lshlrev_b64 v[0:1], 11, v[28:29]
	v_lshl_add_u64 v[0:1], s[20:21], 0, v[0:1]
	v_readlane_b32 s20, v253, 52
	v_lshl_add_u64 v[0:1], v[0:1], 0, v[2:3]
	v_readlane_b32 s21, v253, 53
	v_readlane_b32 s44, v254, 0
	v_readlane_b32 s45, v254, 1
	v_lshl_add_u64 v[38:39], s[20:21], 0, v[0:1]
	v_lshlrev_b64 v[0:1], 12, v[28:29]
	s_add_u32 s26, s44, s0
	v_lshl_add_u64 v[0:1], s[0:1], 0, v[0:1]
	v_readlane_b32 s48, v254, 4
	v_readlane_b32 s49, v254, 5
	v_readlane_b32 s50, v254, 6
	v_readlane_b32 s51, v254, 7
	s_addc_u32 s27, s45, s1
	s_ashr_i32 s23, s22, 31
	v_lshl_add_u64 v[0:1], v[0:1], 0, v[168:169]
	v_lshl_add_u64 v[30:31], s[26:27], 0, v[168:169]
	v_lshl_add_u64 v[34:35], s[48:49], 0, v[168:169]
	v_lshl_add_u64 v[36:37], s[50:51], 0, v[168:169]
	s_lshl_b64 s[20:21], s[22:23], 11
	v_lshl_add_u64 v[40:41], s[44:45], 0, v[0:1]
	s_lshl_b64 s[24:25], s[22:23], 12
	s_mov_b64 s[26:27], 0
	v_readlane_b32 s46, v254, 2
	v_readlane_b32 s47, v254, 3
	v_readlane_b32 s52, v254, 8
	v_readlane_b32 s53, v254, 9
	v_readlane_b32 s54, v254, 10
	v_readlane_b32 s55, v254, 11
	v_readlane_b32 s56, v254, 12
	v_readlane_b32 s57, v254, 13
	v_readlane_b32 s58, v254, 14
	v_readlane_b32 s59, v254, 15
	global_load_dwordx4 v[100:103], v[34:35], off
	global_load_dwordx4 v[104:107], v[34:35], off offset:1024
	global_load_dwordx4 v[108:111], v[34:35], off offset:2048
	global_load_dwordx4 v[112:115], v[34:35], off offset:3072
	global_load_dwordx4 v[116:119], v[36:37], off
	global_load_dwordx4 v[120:123], v[36:37], off offset:1024
	global_load_dwordx4 v[124:127], v[36:37], off offset:2048
	global_load_dwordx4 v[128:131], v[36:37], off offset:3072
	v_add_u32_e32 v164, 0x8000, v28
	v_ashrrev_i32_e32 v165, 31, v164
	v_lshlrev_b64 v[164:165], 12, v[164:165]
	v_lshl_add_u64 v[164:165], v[30:31], 0, v[164:165]
	global_load_dwordx4 v[132:135], v[40:41], off
	global_load_dwordx4 v[136:139], v[40:41], off offset:1024
	global_load_dwordx4 v[140:143], v[40:41], off offset:2048
	global_load_dwordx4 v[144:147], v[40:41], off offset:3072
	global_load_dwordx4 v[148:151], v[164:165], off
	global_load_dwordx4 v[152:155], v[164:165], off offset:1024
	global_load_dwordx4 v[156:159], v[164:165], off offset:2048
	global_load_dwordx4 v[160:163], v[164:165], off offset:3072
	s_waitcnt vmcnt(0)
	s_branch .Lln_after
.LBB0_1730:
	s_waitcnt vmcnt(8)
.Lln_after:
	v_and_b32_e32 v18, 64, v224
	v_xor_b32_e32 v20, 1, v224
	v_add_u32_e32 v26, 64, v18
	v_xor_b32_e32 v21, 2, v224
	v_cmp_lt_i32_e32 vcc, v20, v26
	v_xor_b32_e32 v22, 4, v224
	v_xor_b32_e32 v23, 8, v224
	v_cndmask_b32_e32 v20, v224, v20, vcc
	v_cmp_lt_i32_e32 vcc, v21, v26
	v_add_u32_e32 v16, 0x8000, v28
	s_mov_b64 s[0:1], 0
	v_cndmask_b32_e32 v21, v224, v21, vcc
	v_cmp_lt_i32_e32 vcc, v22, v26
	s_mov_b64 s[38:39], 0
	v_xor_b32_e32 v24, 16, v224
	v_cndmask_b32_e32 v22, v224, v22, vcc
	v_cmp_lt_i32_e32 vcc, v23, v26
	v_xor_b32_e32 v25, 32, v224
	v_ashrrev_i32_e32 v17, 31, v16
	v_mov_b32_e32 v12, v132
	v_mov_b32_e32 v13, v133
	v_mov_b32_e32 v14, v134
	v_mov_b32_e32 v15, v135
	v_mov_b32_e32 v8, v136
	v_mov_b32_e32 v9, v137
	v_mov_b32_e32 v10, v138
	v_mov_b32_e32 v11, v139
	v_mov_b32_e32 v4, v140
	v_mov_b32_e32 v5, v141
	v_mov_b32_e32 v6, v142
	v_mov_b32_e32 v7, v143
	v_mov_b32_e32 v0, v144
	v_mov_b32_e32 v1, v145
	v_mov_b32_e32 v2, v146
	v_mov_b32_e32 v3, v147
	v_cndmask_b32_e32 v23, v224, v23, vcc
	v_cmp_lt_i32_e32 vcc, v24, v26
	v_lshlrev_b64 v[18:19], 12, v[16:17]
	v_lshlrev_b64 v[16:17], 11, v[16:17]
	v_cndmask_b32_e32 v24, v224, v24, vcc
	v_cmp_lt_i32_e32 vcc, v25, v26
	v_lshl_add_u64 v[44:45], v[34:35], 0, s[0:1]
	v_lshl_add_u64 v[18:19], v[30:31], 0, v[18:19]
	v_cndmask_b32_e32 v25, v224, v25, vcc
	v_lshl_add_u64 v[46:47], v[36:37], 0, s[38:39]
	v_lshlrev_b32_e32 v29, 2, v20
	v_lshlrev_b32_e32 v80, 2, v21
	v_lshlrev_b32_e32 v81, 2, v22
	v_lshlrev_b32_e32 v82, 2, v23
	v_lshlrev_b32_e32 v83, 2, v24
	v_lshlrev_b32_e32 v84, 2, v25
	v_lshl_add_u64 v[42:43], v[32:33], 0, v[16:17]
	v_mov_b32_e32 v48, v100
	v_mov_b32_e32 v49, v101
	v_mov_b32_e32 v50, v102
	v_mov_b32_e32 v51, v103
	v_mov_b32_e32 v52, v116
	v_mov_b32_e32 v53, v117
	v_mov_b32_e32 v54, v118
	v_mov_b32_e32 v55, v119
	v_mov_b32_e32 v56, v148
	v_mov_b32_e32 v57, v149
	v_mov_b32_e32 v58, v150
	v_mov_b32_e32 v59, v151
	v_mov_b32_e32 v24, v152
	v_mov_b32_e32 v25, v153
	v_mov_b32_e32 v26, v154
	v_mov_b32_e32 v27, v155
	v_mov_b32_e32 v20, v156
	v_mov_b32_e32 v21, v157
	v_mov_b32_e32 v22, v158
	v_mov_b32_e32 v23, v159
	s_nop 0
	v_mov_b32_e32 v16, v160
	v_mov_b32_e32 v17, v161
	v_mov_b32_e32 v18, v162
	v_mov_b32_e32 v19, v163
	v_add_u32_e32 v28, s22, v28
	v_lshl_add_u64 v[40:41], v[40:41], 0, s[24:25]
	v_cmp_ge_i32_e32 vcc, s96, v28
	s_cbranch_vccz .Lln_nopf
	v_add_u32_e32 v164, 0x8000, v28
	v_ashrrev_i32_e32 v165, 31, v164
	v_lshlrev_b64 v[164:165], 12, v[164:165]
	v_lshl_add_u64 v[164:165], v[30:31], 0, v[164:165]
	global_load_dwordx4 v[132:135], v[40:41], off
	global_load_dwordx4 v[136:139], v[40:41], off offset:1024
	global_load_dwordx4 v[140:143], v[40:41], off offset:2048
	global_load_dwordx4 v[144:147], v[40:41], off offset:3072
	global_load_dwordx4 v[148:151], v[164:165], off
	global_load_dwordx4 v[152:155], v[164:165], off offset:1024
	global_load_dwordx4 v[156:159], v[164:165], off offset:2048
	global_load_dwordx4 v[160:163], v[164:165], off offset:3072
.Lln_nopf:
	v_mov_b32_e32 v60, v13
	v_mov_b32_e32 v61, v14
	v_mov_b32_e32 v62, v12
	v_mov_b32_e32 v63, v15
	v_mov_b32_e32 v64, v9
	v_mov_b32_e32 v65, v10
	v_mov_b32_e32 v66, v8
	v_mov_b32_e32 v67, v11
	v_pk_add_f32 v[60:61], v[60:61], v[62:63]
	v_pk_add_f32 v[62:63], v[64:65], v[66:67]
	v_add_f32_e32 v68, v4, v5
	v_add_f32_e32 v70, v6, v7
	v_mov_b32_e32 v69, v2
	v_mov_b32_e32 v71, v3
	v_add_f32_e32 v66, v60, v61
	v_pk_add_f32 v[60:61], v[62:63], v[62:63] op_sel:[0,1] op_sel_hi:[1,0]
	v_mov_b32_e32 v73, v0
	v_pk_add_f32 v[64:65], v[68:69], v[70:71]
	v_add_f32_e32 v72, 0, v66
	v_mov_b32_e32 v62, v57
	v_mov_b32_e32 v63, v58
	v_mov_b32_e32 v66, v56
	v_mov_b32_e32 v67, v59
	v_mov_b32_e32 v68, v25
	v_mov_b32_e32 v69, v26
	v_mov_b32_e32 v70, v24
	v_mov_b32_e32 v71, v27
	v_mov_b32_e32 v61, v1
	v_pk_add_f32 v[62:63], v[62:63], v[66:67]
	v_pk_add_f32 v[66:67], v[68:69], v[70:71]
	v_pk_add_f32 v[60:61], v[72:73], v[60:61]
	v_add_f32_e32 v70, v62, v63
	v_pk_add_f32 v[62:63], v[66:67], v[66:67] op_sel:[0,1] op_sel_hi:[1,0]
	v_pk_add_f32 v[60:61], v[60:61], v[64:65]
	v_add_f32_e32 v74, v20, v21
	v_add_f32_e32 v76, v22, v23
	v_mov_b32_e32 v79, v16
	v_mov_b32_e32 v75, v18
	v_mov_b32_e32 v77, v19
	v_add_f32_e32 v78, 0, v70
	v_add_f32_e32 v64, v60, v61
	v_mov_b32_e32 v63, v17
	v_pk_add_f32 v[68:69], v[74:75], v[76:77]
	ds_bpermute_b32 v65, v29, v64
	v_pk_add_f32 v[60:61], v[78:79], v[62:63]
	s_waitcnt lgkmcnt(0)
	v_add_f32_e32 v62, v64, v65
	v_pk_add_f32 v[60:61], v[60:61], v[68:69]
	ds_bpermute_b32 v63, v80, v62
	v_add_f32_e32 v60, v60, v61
	ds_bpermute_b32 v61, v29, v60
	s_waitcnt lgkmcnt(1)
	v_add_f32_e32 v62, v62, v63
	ds_bpermute_b32 v63, v81, v62
	s_waitcnt lgkmcnt(1)
	v_add_f32_e32 v60, v60, v61
	ds_bpermute_b32 v61, v80, v60
	s_waitcnt lgkmcnt(1)
	v_add_f32_e32 v62, v62, v63
	ds_bpermute_b32 v63, v82, v62
	s_waitcnt lgkmcnt(1)
	v_add_f32_e32 v60, v60, v61
	ds_bpermute_b32 v61, v81, v60
	s_waitcnt lgkmcnt(1)
	v_add_f32_e32 v62, v62, v63
	ds_bpermute_b32 v63, v83, v62
	s_waitcnt lgkmcnt(1)
	v_add_f32_e32 v60, v60, v61
	ds_bpermute_b32 v61, v82, v60
	s_waitcnt lgkmcnt(1)
	v_add_f32_e32 v62, v62, v63
	ds_bpermute_b32 v63, v84, v62
	s_waitcnt lgkmcnt(1)
	v_add_f32_e32 v60, v60, v61
	ds_bpermute_b32 v61, v83, v60
	s_waitcnt lgkmcnt(1)
	v_add_f32_e32 v62, v62, v63
	v_fmamk_f32 v13, v62, 0xba800000, v13
	s_waitcnt lgkmcnt(0)
	v_add_f32_e32 v69, v60, v61
	ds_bpermute_b32 v71, v84, v69
	v_fmamk_f32 v12, v62, 0xba800000, v12
	v_fmamk_f32 v15, v62, 0xba800000, v15
	v_fmac_f32_e32 v14, 0xba800000, v62
	v_fmamk_f32 v9, v62, 0xba800000, v9
	v_fmamk_f32 v8, v62, 0xba800000, v8
	v_fmamk_f32 v11, v62, 0xba800000, v11
	v_fmac_f32_e32 v10, 0xba800000, v62
	v_fmamk_f32 v61, v62, 0xba800000, v5
	v_fmamk_f32 v60, v62, 0xba800000, v4
	v_fmamk_f32 v7, v62, 0xba800000, v7
	v_fmac_f32_e32 v6, 0xba800000, v62
	v_fmamk_f32 v3, v62, 0xba800000, v3
	v_fmamk_f32 v2, v62, 0xba800000, v2
	v_fmamk_f32 v1, v62, 0xba800000, v1
	v_fmac_f32_e32 v0, 0xba800000, v62
	v_pk_mul_f32 v[4:5], v[14:15], v[14:15]
	v_pk_mul_f32 v[62:63], v[12:13], v[12:13]
	v_pk_mul_f32 v[64:65], v[10:11], v[10:11]
	v_pk_mul_f32 v[66:67], v[8:9], v[8:9]
	v_mul_f32_e32 v68, v60, v60
	v_mul_f32_e32 v70, v6, v6
	s_waitcnt lgkmcnt(0)
	v_add_f32_e32 v74, v69, v71
	v_pk_mov_b32 v[72:73], v[62:63], v[4:5] op_sel:[1,0]
	v_mov_b32_e32 v63, v5
	v_pk_mov_b32 v[4:5], v[66:67], v[64:65] op_sel:[1,0]
	v_mov_b32_e32 v67, v65
	v_pk_fma_f32 v[64:65], v[60:61], v[60:61], v[68:69] op_sel_hi:[1,1,0]
	v_pk_fma_f32 v[68:69], v[6:7], v[6:7], v[70:71] op_sel_hi:[1,1,0]
	v_fmamk_f32 v57, v74, 0xba800000, v57
	v_fmamk_f32 v56, v74, 0xba800000, v56
	v_fmamk_f32 v59, v74, 0xba800000, v59
	v_fmac_f32_e32 v58, 0xba800000, v74
	v_pk_add_f32 v[62:63], v[62:63], v[72:73]
	v_fmamk_f32 v25, v74, 0xba800000, v25
	v_fmamk_f32 v24, v74, 0xba800000, v24
	v_fmamk_f32 v27, v74, 0xba800000, v27
	v_fmac_f32_e32 v26, 0xba800000, v74
	v_pk_add_f32 v[66:67], v[66:67], v[4:5]
	v_fmamk_f32 v71, v74, 0xba800000, v21
	v_fmamk_f32 v70, v74, 0xba800000, v20
	v_fmamk_f32 v23, v74, 0xba800000, v23
	v_fmac_f32_e32 v22, 0xba800000, v74
	v_fmamk_f32 v5, v74, 0xba800000, v19
	v_fmamk_f32 v4, v74, 0xba800000, v18
	v_fmamk_f32 v17, v74, 0xba800000, v17
	v_fmac_f32_e32 v16, 0xba800000, v74
	v_mul_f32_e32 v64, v0, v0
	v_mul_f32_e32 v68, v1, v1
	v_pk_add_f32 v[18:19], v[62:63], v[62:63] op_sel_hi:[0,1]
	v_pk_mul_f32 v[20:21], v[58:59], v[58:59]
	v_pk_mul_f32 v[62:63], v[56:57], v[56:57]
	v_pk_mul_f32 v[72:73], v[26:27], v[26:27]
	v_pk_mul_f32 v[74:75], v[24:25], v[24:25]
	v_pk_add_f32 v[66:67], v[66:67], v[66:67] op_sel_hi:[0,1]
	v_pk_add_f32 v[64:65], v[64:65], v[68:69]
	v_pk_mov_b32 v[68:69], v[62:63], v[20:21] op_sel:[1,0]
	v_mov_b32_e32 v63, v21
	v_pk_mov_b32 v[20:21], v[74:75], v[72:73] op_sel:[1,0]
	v_mov_b32_e32 v75, v73
	v_mul_f32_e32 v18, v70, v70
	v_mul_f32_e32 v66, v22, v22
	v_pk_add_f32 v[62:63], v[68:69], v[62:63]
	v_pk_add_f32 v[20:21], v[20:21], v[74:75]
	v_pk_fma_f32 v[72:73], v[70:71], v[70:71], v[18:19] op_sel_hi:[1,1,0]
	v_pk_fma_f32 v[76:77], v[22:23], v[22:23], v[66:67] op_sel_hi:[1,1,0]
	v_mul_f32_e32 v66, v2, v2
	v_mul_f32_e32 v18, v3, v3
	v_pk_add_f32 v[62:63], v[62:63], v[62:63] op_sel_hi:[0,1]
	v_pk_add_f32 v[20:21], v[20:21], v[20:21] op_sel_hi:[0,1]
	v_pk_add_f32 v[18:19], v[18:19], v[66:67]
	v_mul_f32_e32 v72, v16, v16
	v_mul_f32_e32 v76, v17, v17
	v_mul_f32_e32 v62, v4, v4
	v_mul_f32_e32 v20, v5, v5
	v_pk_add_f32 v[18:19], v[64:65], v[18:19]
	v_pk_add_f32 v[64:65], v[72:73], v[76:77]
	v_pk_add_f32 v[20:21], v[62:63], v[20:21]
	v_mov_b32_e32 v67, v18
	v_pk_add_f32 v[20:21], v[64:65], v[20:21]
	s_nop 0
	v_mov_b32_e32 v66, v20
	v_mov_b32_e32 v18, v21
	v_pk_add_f32 v[18:19], v[66:67], v[18:19]
	ds_bpermute_b32 v21, v29, v19
	ds_bpermute_b32 v20, v29, v18
	s_waitcnt lgkmcnt(0)
	v_pk_add_f32 v[18:19], v[18:19], v[20:21]
	ds_bpermute_b32 v21, v80, v19
	ds_bpermute_b32 v20, v80, v18
	s_waitcnt lgkmcnt(0)
	v_pk_add_f32 v[18:19], v[18:19], v[20:21]
	ds_bpermute_b32 v21, v81, v19
	ds_bpermute_b32 v20, v81, v18
	s_waitcnt lgkmcnt(0)
	v_pk_add_f32 v[18:19], v[18:19], v[20:21]
	ds_bpermute_b32 v21, v82, v19
	ds_bpermute_b32 v20, v82, v18
	s_waitcnt lgkmcnt(0)
	v_pk_add_f32 v[18:19], v[18:19], v[20:21]
	ds_bpermute_b32 v21, v83, v19
	ds_bpermute_b32 v20, v83, v18
	s_waitcnt lgkmcnt(0)
	v_pk_add_f32 v[18:19], v[18:19], v[20:21]
	ds_bpermute_b32 v21, v84, v19
	ds_bpermute_b32 v20, v84, v18
	s_waitcnt lgkmcnt(0)
	v_pk_add_f32 v[18:19], v[18:19], v[20:21]
	s_nop 0
	v_pk_fma_f32 v[18:19], v[18:19], s[40:41], v[180:181] op_sel_hi:[1,0,0]
	s_nop 0
	v_mul_f32_e32 v20, 0x4b800000, v19
	v_cmp_gt_f32_e64 s[0:1], s34, v19
	v_mul_f32_e32 v21, 0x4b800000, v18
	v_cmp_gt_f32_e32 vcc, s34, v18
	v_cndmask_b32_e64 v19, v19, v20, s[0:1]
	v_rsq_f32_e32 v19, v19
	v_cndmask_b32_e32 v18, v18, v21, vcc
	v_rsq_f32_e32 v18, v18
	v_mul_f32_e32 v20, 0x45800000, v19
	v_cndmask_b32_e64 v62, v19, v20, s[0:1]
	v_mul_f32_e32 v21, 0x45800000, v18
	v_cndmask_b32_e32 v64, v18, v21, vcc
	v_pk_mul_f32 v[12:13], v[12:13], v[62:63] op_sel_hi:[1,0]
	v_pk_mul_f32 v[14:15], v[14:15], v[62:63] op_sel_hi:[1,0]
	v_pk_mul_f32 v[18:19], v[56:57], v[64:65] op_sel_hi:[1,0]
	v_pk_mul_f32 v[20:21], v[58:59], v[64:65] op_sel_hi:[1,0]
	v_pk_fma_f32 v[14:15], v[50:51], v[14:15], v[54:55]
	v_pk_fma_f32 v[12:13], v[48:49], v[12:13], v[52:53]
	v_pk_fma_f32 v[20:21], v[50:51], v[20:21], v[54:55]
	v_pk_fma_f32 v[18:19], v[48:49], v[18:19], v[52:53]
	v_cvt_pk_bf16_f32 v12, v12, v13
	v_cvt_pk_bf16_f32 v13, v14, v15
	v_cvt_pk_bf16_f32 v14, v18, v19
	v_cvt_pk_bf16_f32 v15, v20, v21
	global_store_dwordx2 v[38:39], v[12:13], off offset:-1024
	global_store_dwordx2 v[42:43], v[14:15], off
	v_mov_b32_e32 v12, v104
	v_mov_b32_e32 v13, v105
	v_mov_b32_e32 v14, v106
	v_mov_b32_e32 v15, v107
	s_nop 0
	v_mov_b32_e32 v18, v120
	v_mov_b32_e32 v19, v121
	v_mov_b32_e32 v20, v122
	v_mov_b32_e32 v21, v123
	v_pk_mul_f32 v[8:9], v[8:9], v[62:63] op_sel_hi:[1,0]
	v_pk_mul_f32 v[10:11], v[10:11], v[62:63] op_sel_hi:[1,0]
	v_pk_mul_f32 v[24:25], v[24:25], v[64:65] op_sel_hi:[1,0]
	v_pk_mul_f32 v[26:27], v[26:27], v[64:65] op_sel_hi:[1,0]
	v_pk_mul_f32 v[6:7], v[6:7], v[62:63] op_sel_hi:[1,0]
	v_pk_mul_f32 v[22:23], v[22:23], v[64:65] op_sel_hi:[1,0]
	v_pk_mul_f32 v[0:1], v[0:1], v[62:63] op_sel_hi:[1,0]
	v_pk_mul_f32 v[2:3], v[2:3], v[62:63] op_sel_hi:[1,0]
	v_pk_mul_f32 v[4:5], v[4:5], v[64:65] op_sel_hi:[1,0]
	v_cmp_lt_i32_e32 vcc, s96, v28
	s_or_b64 s[26:27], vcc, s[26:27]
	v_pk_fma_f32 v[10:11], v[14:15], v[10:11], v[20:21]
	v_pk_fma_f32 v[8:9], v[12:13], v[8:9], v[18:19]
	v_pk_fma_f32 v[14:15], v[14:15], v[26:27], v[20:21]
	v_pk_fma_f32 v[12:13], v[12:13], v[24:25], v[18:19]
	v_cvt_pk_bf16_f32 v8, v8, v9
	v_cvt_pk_bf16_f32 v9, v10, v11
	v_cvt_pk_bf16_f32 v10, v12, v13
	v_cvt_pk_bf16_f32 v11, v14, v15
	global_store_dwordx2 v[38:39], v[8:9], off offset:-512
	global_store_dwordx2 v[42:43], v[10:11], off offset:512
	v_mov_b32_e32 v8, v108
	v_mov_b32_e32 v9, v109
	v_mov_b32_e32 v10, v110
	v_mov_b32_e32 v11, v111
	s_nop 0
	v_mov_b32_e32 v12, v124
	v_mov_b32_e32 v13, v125
	v_mov_b32_e32 v14, v126
	v_mov_b32_e32 v15, v127
	v_pk_mul_f32 v[18:19], v[60:61], v[62:63] op_sel_hi:[1,0]
	v_pk_mul_f32 v[20:21], v[70:71], v[64:65] op_sel_hi:[1,0]
	v_pk_fma_f32 v[6:7], v[10:11], v[6:7], v[14:15]
	v_pk_fma_f32 v[18:19], v[8:9], v[18:19], v[12:13]
	v_pk_fma_f32 v[10:11], v[10:11], v[22:23], v[14:15]
	v_pk_fma_f32 v[8:9], v[8:9], v[20:21], v[12:13]
	v_cvt_pk_bf16_f32 v7, v6, v7
	v_cvt_pk_bf16_f32 v6, v18, v19
	v_cvt_pk_bf16_f32 v8, v8, v9
	v_cvt_pk_bf16_f32 v9, v10, v11
	global_store_dwordx2 v[38:39], v[6:7], off
	global_store_dwordx2 v[42:43], v[8:9], off offset:1024
	v_mov_b32_e32 v6, v112
	v_mov_b32_e32 v7, v113
	v_mov_b32_e32 v8, v114
	v_mov_b32_e32 v9, v115
	s_nop 0
	v_mov_b32_e32 v10, v128
	v_mov_b32_e32 v11, v129
	v_mov_b32_e32 v12, v130
	v_mov_b32_e32 v13, v131
	v_pk_mul_f32 v[14:15], v[16:17], v[64:65] op_sel_hi:[1,0]
	v_pk_fma_f32 v[2:3], v[8:9], v[2:3], v[12:13]
	v_pk_fma_f32 v[0:1], v[6:7], v[0:1], v[10:11]
	v_pk_fma_f32 v[4:5], v[8:9], v[4:5], v[12:13]
	v_pk_fma_f32 v[6:7], v[6:7], v[14:15], v[10:11]
	v_cvt_pk_bf16_f32 v0, v0, v1
	v_cvt_pk_bf16_f32 v1, v2, v3
	v_cvt_pk_bf16_f32 v2, v6, v7
	v_cvt_pk_bf16_f32 v3, v4, v5
	global_store_dwordx2 v[38:39], v[0:1], off offset:512
	global_store_dwordx2 v[42:43], v[2:3], off offset:1536
	v_lshl_add_u64 v[38:39], v[38:39], 0, s[20:21]
	s_andn2_b64 exec, exec, s[26:27]
	s_cbranch_execnz .LBB0_1730
.LBB0_1731:
	s_or_b64 exec, exec, s[2:3]
	s_cmp_eq_u32 s32, 1
	s_cbranch_scc0 .Lp0_ln_done
	s_mov_b32 s32, 2
	v_mov_b32_e32 v0, v95
	v_mov_b32_e32 v1, v96
	v_mov_b32_e32 v14, v97
	v_mov_b32_e32 v15, v98
	v_mov_b32_e32 v29, v99
	s_mov_b32 s23, s68
	s_branch .Lp0_norm
.Lp0_ln_done:
	s_mov_b32 s32, 0
	v_readlane_b32 s24, v254, 37
	v_readlane_b32 s25, v254, 38
